# finalize_qkv V pass rewritten by hand: 64 independent 2-byte loads in flight per item instead of 64 dependent load/wait round trips, readlane broadcasts instead of 64 ds_bpermute (bit-identical math)
# speedup vs baseline: 1.0022x; 1.0022x over previous
; __device__ __forceinline__ unsigned cvtpk(float lo, float hi) { f32x2_t v = {lo, hi}; bf16x2_t b = __builtin_convertvector(v, bf16x2_t); return __builtin_bit_cast(unsigned, b); }
; __device__ __forceinline__ void finalize_qkv(const bf16_t* QP, const bf16_t* KVP, const float* ZRp, const float* RQ, const float* RKV, const float* ROPE,
;                                              const float* qn, const float* kn, bf16_t* Qb, bf16_t* Kimg, bf16_t* Vimg, int gw, int NGW, int lane) {
;     ...
;     for (int it = gw; it < (SEQ / 16) * 2; it += NGW) {
;         const int g = it >> 1, hh = it & 1; const int tok0 = g * 16; const float rl = RKV[tok0 + (lane & 15)];
; #pragma unroll
;         for (int h4 = 0; h4 < 4; ++h4) { const int hd = hh * 4 + h4;
; #pragma unroll
;             for (int hi = 0; hi < 2; ++hi) { float e[8];
; #pragma unroll
;                 for (int j = 0; j < 8; ++j) { const int t = 8 * (j >> 2) + 4 * hi + (j & 3); e[j] = bf2f(KVP[(size_t)(tok0 + t) * 1024 + 512 + hd * 64 + lane]) * __shfl(rl, t); }
;                 *(u32x4*)(Vimg + ((size_t)hd * 256 + (g >> 2)) * 4096 + ((size_t)((g & 3) * 2 + hi) * 64 + lane) * 8) = (u32x4){cvtpk(e[0], e[1]), cvtpk(e[2], e[3]), cvtpk(e[4], e[5]), cvtpk(e[6], e[7])}; } }
;     }
.LBB0_868:
	s_waitcnt vmcnt(0)
	s_lshr_b32 s0, s89, 1
	s_and_b32 s1, s89, 1
	s_lshl_b32 s2, s0, 4
	v_or_b32_e32 v2, s2, v36
	v_mov_b32_e32 v3, 0
	v_lshl_add_u64 v[2:3], v[2:3], 2, s[14:15]
	global_load_dword v35, v[2:3], off
	s_lshl_b32 s3, s2, 11
	s_lshl_b32 s16, s1, 9
	s_add_u32 s3, s3, s16
	s_add_u32 s20, s18, s3
	s_addc_u32 s21, s19, 0
	global_load_ushort v64, v160, s[20:21] offset:1024
	global_load_ushort v80, v160, s[20:21] offset:1152
	global_load_ushort v96, v160, s[20:21] offset:1280
	global_load_ushort v112, v160, s[20:21] offset:1408
	s_add_u32 s20, s20, 0x800
	s_addc_u32 s21, s21, 0
	global_load_ushort v65, v160, s[20:21] offset:1024
	global_load_ushort v81, v160, s[20:21] offset:1152
	global_load_ushort v97, v160, s[20:21] offset:1280
	global_load_ushort v113, v160, s[20:21] offset:1408
	s_add_u32 s20, s20, 0x800
	s_addc_u32 s21, s21, 0
	global_load_ushort v66, v160, s[20:21] offset:1024
	global_load_ushort v82, v160, s[20:21] offset:1152
	global_load_ushort v98, v160, s[20:21] offset:1280
	global_load_ushort v114, v160, s[20:21] offset:1408
	s_add_u32 s20, s20, 0x800
	s_addc_u32 s21, s21, 0
	global_load_ushort v67, v160, s[20:21] offset:1024
	global_load_ushort v83, v160, s[20:21] offset:1152
	global_load_ushort v99, v160, s[20:21] offset:1280
	global_load_ushort v115, v160, s[20:21] offset:1408
	s_add_u32 s20, s20, 0x800
	s_addc_u32 s21, s21, 0
	global_load_ushort v68, v160, s[20:21] offset:1024
	global_load_ushort v84, v160, s[20:21] offset:1152
	global_load_ushort v100, v160, s[20:21] offset:1280
	global_load_ushort v116, v160, s[20:21] offset:1408
	s_add_u32 s20, s20, 0x800
	s_addc_u32 s21, s21, 0
	global_load_ushort v69, v160, s[20:21] offset:1024
	global_load_ushort v85, v160, s[20:21] offset:1152
	global_load_ushort v101, v160, s[20:21] offset:1280
	global_load_ushort v117, v160, s[20:21] offset:1408
	s_add_u32 s20, s20, 0x800
	s_addc_u32 s21, s21, 0
	global_load_ushort v70, v160, s[20:21] offset:1024
	global_load_ushort v86, v160, s[20:21] offset:1152
	global_load_ushort v102, v160, s[20:21] offset:1280
	global_load_ushort v118, v160, s[20:21] offset:1408
	s_add_u32 s20, s20, 0x800
	s_addc_u32 s21, s21, 0
	global_load_ushort v71, v160, s[20:21] offset:1024
	global_load_ushort v87, v160, s[20:21] offset:1152
	global_load_ushort v103, v160, s[20:21] offset:1280
	global_load_ushort v119, v160, s[20:21] offset:1408
	s_add_u32 s20, s20, 0x800
	s_addc_u32 s21, s21, 0
	global_load_ushort v72, v160, s[20:21] offset:1024
	global_load_ushort v88, v160, s[20:21] offset:1152
	global_load_ushort v104, v160, s[20:21] offset:1280
	global_load_ushort v120, v160, s[20:21] offset:1408
	s_add_u32 s20, s20, 0x800
	s_addc_u32 s21, s21, 0
	global_load_ushort v73, v160, s[20:21] offset:1024
	global_load_ushort v89, v160, s[20:21] offset:1152
	global_load_ushort v105, v160, s[20:21] offset:1280
	global_load_ushort v121, v160, s[20:21] offset:1408
	s_add_u32 s20, s20, 0x800
	s_addc_u32 s21, s21, 0
	global_load_ushort v74, v160, s[20:21] offset:1024
	global_load_ushort v90, v160, s[20:21] offset:1152
	global_load_ushort v106, v160, s[20:21] offset:1280
	global_load_ushort v122, v160, s[20:21] offset:1408
	s_add_u32 s20, s20, 0x800
	s_addc_u32 s21, s21, 0
	global_load_ushort v75, v160, s[20:21] offset:1024
	global_load_ushort v91, v160, s[20:21] offset:1152
	global_load_ushort v107, v160, s[20:21] offset:1280
	global_load_ushort v123, v160, s[20:21] offset:1408
	s_add_u32 s20, s20, 0x800
	s_addc_u32 s21, s21, 0
	global_load_ushort v76, v160, s[20:21] offset:1024
	global_load_ushort v92, v160, s[20:21] offset:1152
	global_load_ushort v108, v160, s[20:21] offset:1280
	global_load_ushort v124, v160, s[20:21] offset:1408
	s_add_u32 s20, s20, 0x800
	s_addc_u32 s21, s21, 0
	global_load_ushort v77, v160, s[20:21] offset:1024
	global_load_ushort v93, v160, s[20:21] offset:1152
	global_load_ushort v109, v160, s[20:21] offset:1280
	global_load_ushort v125, v160, s[20:21] offset:1408
	s_add_u32 s20, s20, 0x800
	s_addc_u32 s21, s21, 0
	global_load_ushort v78, v160, s[20:21] offset:1024
	global_load_ushort v94, v160, s[20:21] offset:1152
	global_load_ushort v110, v160, s[20:21] offset:1280
	global_load_ushort v126, v160, s[20:21] offset:1408
	s_add_u32 s20, s20, 0x800
	s_addc_u32 s21, s21, 0
	global_load_ushort v79, v160, s[20:21] offset:1024
	global_load_ushort v95, v160, s[20:21] offset:1152
	global_load_ushort v111, v160, s[20:21] offset:1280
	global_load_ushort v127, v160, s[20:21] offset:1408
	s_lshl_b32 s16, s1, 23
	s_lshr_b32 s17, s0, 2
	s_lshl_b32 s17, s17, 13
	s_add_u32 s16, s16, s17
	s_and_b32 s17, s0, 3
	s_lshl_b32 s17, s17, 11
	s_add_u32 s16, s16, s17
	s_add_u32 s24, s28, s16
	s_addc_u32 s25, s29, 0
	v_lshlrev_b32_e32 v14, 1, v37
	s_waitcnt vmcnt(0)
; __device__ __forceinline__ unsigned cvtpk(float lo, float hi) { f32x2_t v = {lo, hi}; bf16x2_t b = __builtin_convertvector(v, bf16x2_t); return __builtin_bit_cast(unsigned, b); }
; __device__ __forceinline__ void finalize_qkv(const bf16_t* QP, const bf16_t* KVP, const float* ZRp, const float* RQ, const float* RKV, const float* ROPE,
;                                              const float* qn, const float* kn, bf16_t* Qb, bf16_t* Kimg, bf16_t* Vimg, int gw, int NGW, int lane) {
;     ...
;     for (int it = gw; it < (SEQ / 16) * 2; it += NGW) {
;         const int g = it >> 1, hh = it & 1; const int tok0 = g * 16; const float rl = RKV[tok0 + (lane & 15)];
; #pragma unroll
;         for (int h4 = 0; h4 < 4; ++h4) { const int hd = hh * 4 + h4;
; #pragma unroll
;             for (int hi = 0; hi < 2; ++hi) { float e[8];
; #pragma unroll
;                 for (int j = 0; j < 8; ++j) { const int t = 8 * (j >> 2) + 4 * hi + (j & 3); e[j] = bf2f(KVP[(size_t)(tok0 + t) * 1024 + 512 + hd * 64 + lane]) * __shfl(rl, t); }
;                 *(u32x4*)(Vimg + ((size_t)hd * 256 + (g >> 2)) * 4096 + ((size_t)((g & 3) * 2 + hi) * 64 + lane) * 8) = (u32x4){cvtpk(e[0], e[1]), cvtpk(e[2], e[3]), cvtpk(e[4], e[5]), cvtpk(e[6], e[7])}; } }
;     }
	v_readlane_b32 s40, v35, 0
	v_readlane_b32 s41, v35, 1
	v_readlane_b32 s42, v35, 2
	v_readlane_b32 s43, v35, 3
	v_readlane_b32 s44, v35, 4
	v_readlane_b32 s45, v35, 5
	v_readlane_b32 s46, v35, 6
	v_readlane_b32 s47, v35, 7
	v_readlane_b32 s48, v35, 8
	v_readlane_b32 s49, v35, 9
	v_readlane_b32 s50, v35, 10
	v_readlane_b32 s51, v35, 11
	v_readlane_b32 s52, v35, 12
	v_readlane_b32 s53, v35, 13
	v_readlane_b32 s54, v35, 14
	v_readlane_b32 s55, v35, 15
	s_nop 1
	v_lshlrev_b32_e32 v2, 16, v64
	v_lshlrev_b32_e32 v3, 16, v65
	v_lshlrev_b32_e32 v4, 16, v66
	v_lshlrev_b32_e32 v5, 16, v67
	v_lshlrev_b32_e32 v6, 16, v72
	v_lshlrev_b32_e32 v7, 16, v73
	v_lshlrev_b32_e32 v8, 16, v74
	v_lshlrev_b32_e32 v9, 16, v75
	v_mul_f32_e32 v2, s40, v2
	v_mul_f32_e32 v3, s41, v3
	v_mul_f32_e32 v4, s42, v4
	v_mul_f32_e32 v5, s43, v5
	v_mul_f32_e32 v6, s48, v6
	v_mul_f32_e32 v7, s49, v7
	v_mul_f32_e32 v8, s50, v8
	v_mul_f32_e32 v9, s51, v9
	v_cvt_pk_bf16_f32 v10, v2, v3
	v_cvt_pk_bf16_f32 v11, v4, v5
	v_cvt_pk_bf16_f32 v12, v6, v7
	v_cvt_pk_bf16_f32 v13, v8, v9
	global_store_dwordx4 v14, v[10:13], s[24:25]
	v_lshlrev_b32_e32 v2, 16, v68
	v_lshlrev_b32_e32 v3, 16, v69
	v_lshlrev_b32_e32 v4, 16, v70
	v_lshlrev_b32_e32 v5, 16, v71
	v_lshlrev_b32_e32 v6, 16, v76
	v_lshlrev_b32_e32 v7, 16, v77
	v_lshlrev_b32_e32 v8, 16, v78
	v_lshlrev_b32_e32 v9, 16, v79
	v_mul_f32_e32 v2, s44, v2
	v_mul_f32_e32 v3, s45, v3
	v_mul_f32_e32 v4, s46, v4
	v_mul_f32_e32 v5, s47, v5
	v_mul_f32_e32 v6, s52, v6
	v_mul_f32_e32 v7, s53, v7
	v_mul_f32_e32 v8, s54, v8
	v_mul_f32_e32 v9, s55, v9
	v_cvt_pk_bf16_f32 v10, v2, v3
	v_cvt_pk_bf16_f32 v11, v4, v5
	v_cvt_pk_bf16_f32 v12, v6, v7
	v_cvt_pk_bf16_f32 v13, v8, v9
	global_store_dwordx4 v14, v[10:13], s[24:25] offset:1024
	s_add_u32 s24, s24, 0x200000
	s_addc_u32 s25, s25, 0
	v_lshlrev_b32_e32 v2, 16, v80
	v_lshlrev_b32_e32 v3, 16, v81
	v_lshlrev_b32_e32 v4, 16, v82
	v_lshlrev_b32_e32 v5, 16, v83
	v_lshlrev_b32_e32 v6, 16, v88
	v_lshlrev_b32_e32 v7, 16, v89
	v_lshlrev_b32_e32 v8, 16, v90
	v_lshlrev_b32_e32 v9, 16, v91
	v_mul_f32_e32 v2, s40, v2
	v_mul_f32_e32 v3, s41, v3
	v_mul_f32_e32 v4, s42, v4
	v_mul_f32_e32 v5, s43, v5
	v_mul_f32_e32 v6, s48, v6
	v_mul_f32_e32 v7, s49, v7
	v_mul_f32_e32 v8, s50, v8
	v_mul_f32_e32 v9, s51, v9
	v_cvt_pk_bf16_f32 v10, v2, v3
	v_cvt_pk_bf16_f32 v11, v4, v5
	v_cvt_pk_bf16_f32 v12, v6, v7
	v_cvt_pk_bf16_f32 v13, v8, v9
	global_store_dwordx4 v14, v[10:13], s[24:25]
	v_lshlrev_b32_e32 v2, 16, v84
	v_lshlrev_b32_e32 v3, 16, v85
	v_lshlrev_b32_e32 v4, 16, v86
	v_lshlrev_b32_e32 v5, 16, v87
	v_lshlrev_b32_e32 v6, 16, v92
	v_lshlrev_b32_e32 v7, 16, v93
	v_lshlrev_b32_e32 v8, 16, v94
	v_lshlrev_b32_e32 v9, 16, v95
	v_mul_f32_e32 v2, s44, v2
	v_mul_f32_e32 v3, s45, v3
	v_mul_f32_e32 v4, s46, v4
	v_mul_f32_e32 v5, s47, v5
	v_mul_f32_e32 v6, s52, v6
	v_mul_f32_e32 v7, s53, v7
	v_mul_f32_e32 v8, s54, v8
	v_mul_f32_e32 v9, s55, v9
	v_cvt_pk_bf16_f32 v10, v2, v3
	v_cvt_pk_bf16_f32 v11, v4, v5
	v_cvt_pk_bf16_f32 v12, v6, v7
	v_cvt_pk_bf16_f32 v13, v8, v9
	global_store_dwordx4 v14, v[10:13], s[24:25] offset:1024
	s_add_u32 s24, s24, 0x200000
	s_addc_u32 s25, s25, 0
	v_lshlrev_b32_e32 v2, 16, v96
	v_lshlrev_b32_e32 v3, 16, v97
	v_lshlrev_b32_e32 v4, 16, v98
	v_lshlrev_b32_e32 v5, 16, v99
	v_lshlrev_b32_e32 v6, 16, v104
	v_lshlrev_b32_e32 v7, 16, v105
	v_lshlrev_b32_e32 v8, 16, v106
	v_lshlrev_b32_e32 v9, 16, v107
	v_mul_f32_e32 v2, s40, v2
	v_mul_f32_e32 v3, s41, v3
	v_mul_f32_e32 v4, s42, v4
	v_mul_f32_e32 v5, s43, v5
	v_mul_f32_e32 v6, s48, v6
	v_mul_f32_e32 v7, s49, v7
	v_mul_f32_e32 v8, s50, v8
	v_mul_f32_e32 v9, s51, v9
	v_cvt_pk_bf16_f32 v10, v2, v3
	v_cvt_pk_bf16_f32 v11, v4, v5
	v_cvt_pk_bf16_f32 v12, v6, v7
	v_cvt_pk_bf16_f32 v13, v8, v9
	global_store_dwordx4 v14, v[10:13], s[24:25]
	v_lshlrev_b32_e32 v2, 16, v100
	v_lshlrev_b32_e32 v3, 16, v101
	v_lshlrev_b32_e32 v4, 16, v102
	v_lshlrev_b32_e32 v5, 16, v103
	v_lshlrev_b32_e32 v6, 16, v108
	v_lshlrev_b32_e32 v7, 16, v109
	v_lshlrev_b32_e32 v8, 16, v110
	v_lshlrev_b32_e32 v9, 16, v111
	v_mul_f32_e32 v2, s44, v2
	v_mul_f32_e32 v3, s45, v3
	v_mul_f32_e32 v4, s46, v4
	v_mul_f32_e32 v5, s47, v5
	v_mul_f32_e32 v6, s52, v6
	v_mul_f32_e32 v7, s53, v7
	v_mul_f32_e32 v8, s54, v8
	v_mul_f32_e32 v9, s55, v9
	v_cvt_pk_bf16_f32 v10, v2, v3
	v_cvt_pk_bf16_f32 v11, v4, v5
	v_cvt_pk_bf16_f32 v12, v6, v7
	v_cvt_pk_bf16_f32 v13, v8, v9
	global_store_dwordx4 v14, v[10:13], s[24:25] offset:1024
	s_add_u32 s24, s24, 0x200000
	s_addc_u32 s25, s25, 0
	v_lshlrev_b32_e32 v2, 16, v112
	v_lshlrev_b32_e32 v3, 16, v113
	v_lshlrev_b32_e32 v4, 16, v114
	v_lshlrev_b32_e32 v5, 16, v115
	v_lshlrev_b32_e32 v6, 16, v120
	v_lshlrev_b32_e32 v7, 16, v121
	v_lshlrev_b32_e32 v8, 16, v122
	v_lshlrev_b32_e32 v9, 16, v123
	v_mul_f32_e32 v2, s40, v2
	v_mul_f32_e32 v3, s41, v3
	v_mul_f32_e32 v4, s42, v4
	v_mul_f32_e32 v5, s43, v5
	v_mul_f32_e32 v6, s48, v6
	v_mul_f32_e32 v7, s49, v7
	v_mul_f32_e32 v8, s50, v8
	v_mul_f32_e32 v9, s51, v9
	v_cvt_pk_bf16_f32 v10, v2, v3
	v_cvt_pk_bf16_f32 v11, v4, v5
	v_cvt_pk_bf16_f32 v12, v6, v7
	v_cvt_pk_bf16_f32 v13, v8, v9
	global_store_dwordx4 v14, v[10:13], s[24:25]
	v_lshlrev_b32_e32 v2, 16, v116
	v_lshlrev_b32_e32 v3, 16, v117
	v_lshlrev_b32_e32 v4, 16, v118
	v_lshlrev_b32_e32 v5, 16, v119
	v_lshlrev_b32_e32 v6, 16, v124
	v_lshlrev_b32_e32 v7, 16, v125
	v_lshlrev_b32_e32 v8, 16, v126
	v_lshlrev_b32_e32 v9, 16, v127
	v_mul_f32_e32 v2, s44, v2
	v_mul_f32_e32 v3, s45, v3
	v_mul_f32_e32 v4, s46, v4
	v_mul_f32_e32 v5, s47, v5
	v_mul_f32_e32 v6, s52, v6
	v_mul_f32_e32 v7, s53, v7
	v_mul_f32_e32 v8, s54, v8
	v_mul_f32_e32 v9, s55, v9
	v_cvt_pk_bf16_f32 v10, v2, v3
	v_cvt_pk_bf16_f32 v11, v4, v5
	v_cvt_pk_bf16_f32 v12, v6, v7
	v_cvt_pk_bf16_f32 v13, v8, v9
	global_store_dwordx4 v14, v[10:13], s[24:25] offset:1024
	s_add_i32 s89, s89, s88
	s_cmpk_lt_i32 s89, 0x800
	s_cbranch_scc1 .LBB0_868
